# norm1->channel-DFT seams back to grid barriers (their L2 write-back must retire dirty ACT lines before another XCC writes the ZT overlay); 20 local + 9 grid seams
# baseline (speedup 1.0000x reference)
.Lxb_have:
	v_readfirstlane_b32 s10, v0
	v_readfirstlane_b32 s11, v1
	v_readlane_b32 s8, v240, 60
	s_add_i32 s101, s101, 1
	v_mov_b32_e32 v2, 1
	s_nop 1
	v_mov_b32_e32 v4, s8
	ds_read_b32 v4, v4 offset:8
	v_readlane_b32 s8, v240, 0
	s_nop 0
	s_lshl_b32 s9, s8, 6
	s_add_u32 s9, s9, 0x4000
	s_add_u32 s14, s6, s9
	s_addc_u32 s15, s7, 0
	s_waitcnt lgkmcnt(0)
	v_readfirstlane_b32 s9, v4
	s_cmp_eq_u32 s9, 1
	s_cbranch_scc0 .Lxb_grid
	s_mov_b32 s9, 0x3c7df1f4
	s_bitcmp1_b32 s9, s70
	s_cbranch_scc0 .Lxb_grid
	s_and_b32 s9, s8, 7
	s_lshl_b32 s9, s9, 8
	s_add_u32 s9, s9, 0x12000
	s_add_u32 s12, s6, s9
	s_addc_u32 s13, s7, 0
	s_lshr_b32 s9, s8, 3
	s_lshl_b32 s9, s9, 2
	v_mov_b32_e32 v3, s9
	v_mov_b32_e32 v2, s101
	global_store_dword v3, v2, s[12:13]
	buffer_inv sc1
	s_mov_b32 s9, 0
	s_mov_b32 exec_lo, -1
	s_mov_b32 exec_hi, 0
	v_mbcnt_lo_u32_b32 v3, -1, 0
	v_lshlrev_b32_e32 v3, 2, v3
